# phase 7 scan as a continuous pipeline: LDS planes staged in 16-step halves, double-buffered, by filler instructions inside the step code; global prefetch two halves ahead
# speedup vs baseline: 1.0043x; 1.0043x over previous
.LBB0_588:
	s_barrier
	s_setprio 3
	s_lshr_b32 s13, s33, 2
	s_and_b32 s14, s13, 15
	s_lshr_b32 s15, s13, 4
	s_lshl_b32 s15, s15, 23
	s_lshl_b32 s14, s14, 7
	s_add_u32 s14, s14, s15
	s_and_b32 s15, s33, 3
	s_lshl_b32 s15, s15, 5
	s_add_u32 s18, s15, s14
	v_and_b32_e32 v134, 63, v199
	v_lshrrev_b32_e32 v135, 6, v199
	v_lshrrev_b32_e32 v136, 4, v199
	v_and_b32_e32 v137, 15, v199
	v_lshlrev_b32_e32 v244, 11, v136
	v_lshl_add_u32 v138, v137, 3, v244
	v_add_u32_e32 v138, s14, v138
	v_add_u32_e32 v243, 0x15000000, v138
	v_add_u32_e32 v141, 0xac00000, v138
	v_add_u32_e32 v140, 0x8c00000, v138
	v_add_u32_e32 v139, 0x1fc00000, v138
	v_add_u32_e32 v138, 0x6c00000, v138
	v_lshl_add_u32 v244, v137, 1, v244
	v_add_u32_e32 v244, s18, v244
	v_add_u32_e32 v244, 0x17000000, v244
	v_mul_u32_u24_e32 v245, 0x500, v136
	v_lshl_add_u32 v245, v137, 4, v245
	v_mul_u32_u24_e32 v248, 0x50, v137
	v_lshl_add_u32 v248, v136, 2, v248
	v_add_u32_e32 v248, 0xa000, v248
	v_and_b32_e32 v136, 15, v134
	v_lshlrev_b32_e32 v246, 4, v136
	v_lshrrev_b32_e32 v137, 4, v134
	v_lshl_add_u32 v137, v135, 2, v137
	v_mul_u32_u24_e32 v136, 0x50, v137
	v_add_u32_e32 v247, 0xa000, v136
	v_bfe_u32 v136, v134, 2, 2
	v_lshrrev_b32_e32 v249, 1, v136
	v_and_b32_e32 v136, 1, v136
	v_lshl_or_b32 v249, v136, 1, v249
	v_lshlrev_b32_e32 v249, 11, v249
	v_lshl_add_u32 v249, v137, 1, v249
	s_add_u32 s18, s18, 0x25c00000
	v_add_u32_e32 v249, s18, v249
	s_mov_b64 s[10:11], s[94:95]
	s_mov_b64 s[14:15], s[94:95]
	v_mov_b32_e32 v0, 0
	v_mov_b32_e32 v1, 0
	v_mov_b32_e32 v2, 0
	v_mov_b32_e32 v3, 0
	s_mov_b32 s12, 0
	global_load_dwordx2 v[110:111], v138, s[14:15]
	global_load_dwordx2 v[112:113], v139, s[14:15]
	global_load_dwordx2 v[114:115], v140, s[14:15]
	global_load_dwordx2 v[116:117], v141, s[14:15]
	global_load_dwordx2 v[118:119], v243, s[14:15]
	global_load_ushort v120, v244, s[14:15]
	s_waitcnt vmcnt(0)
	v_lshlrev_b32_e32 v134, 16, v110
	v_and_b32_e32 v135, 0xffff0000, v110
	v_lshlrev_b32_e32 v136, 16, v111
	v_and_b32_e32 v137, 0xffff0000, v111
	ds_write_b128 v245, v[134:137] offset:0
	v_lshlrev_b32_e32 v134, 16, v112
	v_and_b32_e32 v135, 0xffff0000, v112
	v_lshlrev_b32_e32 v136, 16, v113
	v_and_b32_e32 v137, 0xffff0000, v113
	ds_write_b128 v245, v[134:137] offset:256
	v_lshlrev_b32_e32 v134, 16, v114
	v_and_b32_e32 v135, 0xffff0000, v114
	v_lshlrev_b32_e32 v136, 16, v115
	v_and_b32_e32 v137, 0xffff0000, v115
	ds_write_b128 v245, v[134:137] offset:512
	v_lshlrev_b32_e32 v134, 16, v116
	v_and_b32_e32 v135, 0xffff0000, v116
	v_lshlrev_b32_e32 v136, 16, v117
	v_and_b32_e32 v137, 0xffff0000, v117
	ds_write_b128 v245, v[134:137] offset:768
	v_lshlrev_b32_e32 v134, 16, v118
	v_and_b32_e32 v135, 0xffff0000, v118
	v_lshlrev_b32_e32 v136, 16, v119
	v_and_b32_e32 v137, 0xffff0000, v119
	ds_write_b128 v245, v[134:137] offset:1024
	v_lshlrev_b32_e32 v134, 16, v120
	ds_write_b32 v248, v134 offset:0
	s_add_u32 s14, s14, 0x8000
	s_addc_u32 s15, s15, 0
	global_load_dwordx2 v[122:123], v138, s[14:15]
	global_load_dwordx2 v[124:125], v139, s[14:15]
	global_load_dwordx2 v[126:127], v140, s[14:15]
	global_load_dwordx2 v[128:129], v141, s[14:15]
	global_load_dwordx2 v[130:131], v243, s[14:15]
	global_load_ushort v132, v244, s[14:15]
	s_waitcnt lgkmcnt(0)
	s_barrier
	ds_read_b128 v[8:11], v246 offset:0
	ds_read_b128 v[12:15], v246 offset:256
	ds_read_b128 v[16:19], v246 offset:512
	ds_read_b128 v[20:23], v246 offset:768
	ds_read_b128 v[24:27], v246 offset:1024
	ds_read_b128 v[88:91], v247 offset:0
	ds_read_b128 v[28:31], v246 offset:1280
	ds_read_b128 v[32:35], v246 offset:1536
	ds_read_b128 v[36:39], v246 offset:1792
	ds_read_b128 v[40:43], v246 offset:2048
	ds_read_b128 v[44:47], v246 offset:2304
	s_waitcnt lgkmcnt(5)
	v_pk_mul_f32 v[96:97], v[0:1], v[20:21]
	v_pk_fma_f32 v[4:5], v[0:1], v[12:13], v[0:1] neg_lo:[1,0,0] neg_hi:[1,0,0]
	v_pk_fma_f32 v[96:97], v[2:3], v[22:23], v[96:97]
	v_pk_fma_f32 v[6:7], v[2:3], v[14:15], v[2:3] neg_lo:[1,0,0] neg_hi:[1,0,0]
	v_add_f32_e32 v98, v96, v97
	ds_read_b128 v[48:51], v246 offset:2560
	ds_read_b128 v[52:55], v246 offset:2816
	ds_read_b128 v[56:59], v246 offset:3072
	ds_read_b128 v[60:63], v246 offset:3328
	ds_read_b128 v[64:67], v246 offset:3584
	v_add_f32_dpp v98, v98, v98 quad_perm:[1,0,3,2] row_mask:0xf bank_mask:0xf bound_ctrl:1
	v_pk_fma_f32 v[4:5], v[16:17], v[88:89], v[4:5] op_sel_hi:[1,0,1]
	v_pk_fma_f32 v[6:7], v[18:19], v[88:89], v[6:7] op_sel_hi:[1,0,1]
	v_add_f32_dpp v98, v98, v98 quad_perm:[2,3,0,1] row_mask:0xf bank_mask:0xf bound_ctrl:1
	s_nop 1
	v_add_f32_dpp v98, v98, v98 row_half_mirror row_mask:0xf bank_mask:0xf bound_ctrl:1
	s_nop 1
	v_add_f32_dpp v98, v98, v98 row_mirror row_mask:0xf bank_mask:0xf bound_ctrl:1
	s_waitcnt vmcnt(0) lgkmcnt(0)
.Lscan_iter:
	s_waitcnt lgkmcnt(5)
	v_pk_fma_f32 v[0:1], v[98:99], v[24:25], v[4:5] op_sel_hi:[0,1,1] neg_lo:[1,0,0] neg_hi:[1,0,0]
	v_pk_fma_f32 v[2:3], v[98:99], v[26:27], v[6:7] op_sel_hi:[0,1,1] neg_lo:[1,0,0] neg_hi:[1,0,0]
	ds_read_b128 v[68:71], v246 offset:3840
	v_pk_mul_f32 v[96:97], v[0:1], v[40:41]
	ds_read_b128 v[72:75], v246 offset:4096
	v_pk_fma_f32 v[96:97], v[2:3], v[42:43], v[96:97]
	v_pk_fma_f32 v[4:5], v[0:1], v[32:33], v[0:1] neg_lo:[1,0,0] neg_hi:[1,0,0]
	v_add_f32_e32 v98, v96, v97
	v_pk_fma_f32 v[6:7], v[2:3], v[34:35], v[2:3] neg_lo:[1,0,0] neg_hi:[1,0,0]
	ds_read_b128 v[76:79], v246 offset:4352
	v_add_f32_dpp v98, v98, v98 quad_perm:[1,0,3,2] row_mask:0xf bank_mask:0xf bound_ctrl:1
	v_pk_fma_f32 v[4:5], v[36:37], v[88:89], v[4:5] op_sel:[0,1,0] op_sel_hi:[1,1,1]
	v_pk_fma_f32 v[6:7], v[38:39], v[88:89], v[6:7] op_sel:[0,1,0] op_sel_hi:[1,1,1]
	v_add_f32_dpp v98, v98, v98 quad_perm:[2,3,0,1] row_mask:0xf bank_mask:0xf bound_ctrl:1
	v_pk_mul_f32 v[100:101], v[0:1], v[8:9]
	v_pk_fma_f32 v[100:101], v[2:3], v[10:11], v[100:101]
	v_add_f32_dpp v98, v98, v98 row_half_mirror row_mask:0xf bank_mask:0xf bound_ctrl:1
	v_add_f32_e32 v102, v100, v101
	s_add_u32 s14, s14, 0x8000
	s_addc_u32 s15, s15, 0
	v_add_f32_dpp v98, v98, v98 row_mirror row_mask:0xf bank_mask:0xf bound_ctrl:1
	ds_read_b128 v[80:83], v246 offset:4608
	ds_read_b128 v[84:87], v246 offset:4864
	global_load_dwordx2 v[110:111], v138, s[14:15]
	global_load_dwordx2 v[112:113], v139, s[14:15]
	global_load_dwordx2 v[114:115], v140, s[14:15]
	global_load_dwordx2 v[116:117], v141, s[14:15]
	s_waitcnt lgkmcnt(5)
	v_pk_fma_f32 v[0:1], v[98:99], v[44:45], v[4:5] op_sel_hi:[0,1,1] neg_lo:[1,0,0] neg_hi:[1,0,0]
	v_pk_fma_f32 v[2:3], v[98:99], v[46:47], v[6:7] op_sel_hi:[0,1,1] neg_lo:[1,0,0] neg_hi:[1,0,0]
	ds_read_b128 v[8:11], v246 offset:5120
	v_pk_mul_f32 v[96:97], v[0:1], v[60:61]
	ds_read_b128 v[12:15], v246 offset:5376
	v_pk_fma_f32 v[96:97], v[2:3], v[62:63], v[96:97]
	v_pk_fma_f32 v[4:5], v[0:1], v[52:53], v[0:1] neg_lo:[1,0,0] neg_hi:[1,0,0]
	v_add_f32_e32 v98, v96, v97
	v_pk_fma_f32 v[6:7], v[2:3], v[54:55], v[2:3] neg_lo:[1,0,0] neg_hi:[1,0,0]
	ds_read_b128 v[16:19], v246 offset:5632
	v_add_f32_dpp v98, v98, v98 quad_perm:[1,0,3,2] row_mask:0xf bank_mask:0xf bound_ctrl:1
	v_pk_fma_f32 v[4:5], v[56:57], v[90:91], v[4:5] op_sel_hi:[1,0,1]
	v_pk_fma_f32 v[6:7], v[58:59], v[90:91], v[6:7] op_sel_hi:[1,0,1]
	v_add_f32_dpp v98, v98, v98 quad_perm:[2,3,0,1] row_mask:0xf bank_mask:0xf bound_ctrl:1
	v_pk_mul_f32 v[100:101], v[0:1], v[28:29]
	v_pk_fma_f32 v[100:101], v[2:3], v[30:31], v[100:101]
	v_add_f32_dpp v98, v98, v98 row_half_mirror row_mask:0xf bank_mask:0xf bound_ctrl:1
	v_add_f32_e32 v103, v100, v101
	global_load_dwordx2 v[118:119], v243, s[14:15]
	v_add_f32_dpp v98, v98, v98 row_mirror row_mask:0xf bank_mask:0xf bound_ctrl:1
	ds_read_b128 v[20:23], v246 offset:5888
	ds_read_b128 v[24:27], v246 offset:6144
	ds_read_b128 v[92:95], v247 offset:16
	global_load_ushort v120, v244, s[14:15]
	s_waitcnt vmcnt(10)
	v_lshlrev_b32_e32 v134, 16, v122
	v_and_b32_e32 v135, 0xffff0000, v122
	s_waitcnt lgkmcnt(6)
	v_pk_fma_f32 v[0:1], v[98:99], v[64:65], v[4:5] op_sel_hi:[0,1,1] neg_lo:[1,0,0] neg_hi:[1,0,0]
	v_pk_fma_f32 v[2:3], v[98:99], v[66:67], v[6:7] op_sel_hi:[0,1,1] neg_lo:[1,0,0] neg_hi:[1,0,0]
	ds_read_b128 v[28:31], v246 offset:6400
	v_pk_mul_f32 v[96:97], v[0:1], v[80:81]
	ds_read_b128 v[32:35], v246 offset:6656
	v_pk_fma_f32 v[96:97], v[2:3], v[82:83], v[96:97]
	v_pk_fma_f32 v[4:5], v[0:1], v[72:73], v[0:1] neg_lo:[1,0,0] neg_hi:[1,0,0]
	v_add_f32_e32 v98, v96, v97
	v_pk_fma_f32 v[6:7], v[2:3], v[74:75], v[2:3] neg_lo:[1,0,0] neg_hi:[1,0,0]
	ds_read_b128 v[36:39], v246 offset:6912
	v_add_f32_dpp v98, v98, v98 quad_perm:[1,0,3,2] row_mask:0xf bank_mask:0xf bound_ctrl:1
	v_pk_fma_f32 v[4:5], v[76:77], v[90:91], v[4:5] op_sel:[0,1,0] op_sel_hi:[1,1,1]
	v_pk_fma_f32 v[6:7], v[78:79], v[90:91], v[6:7] op_sel:[0,1,0] op_sel_hi:[1,1,1]
	v_add_f32_dpp v98, v98, v98 quad_perm:[2,3,0,1] row_mask:0xf bank_mask:0xf bound_ctrl:1
	v_pk_mul_f32 v[100:101], v[0:1], v[48:49]
	v_pk_fma_f32 v[100:101], v[2:3], v[50:51], v[100:101]
	v_add_f32_dpp v98, v98, v98 row_half_mirror row_mask:0xf bank_mask:0xf bound_ctrl:1
	v_add_f32_e32 v104, v100, v101
	v_lshlrev_b32_e32 v136, 16, v123
	v_add_f32_dpp v98, v98, v98 row_mirror row_mask:0xf bank_mask:0xf bound_ctrl:1
	ds_read_b128 v[40:43], v246 offset:7168
	ds_read_b128 v[44:47], v246 offset:7424
	v_and_b32_e32 v137, 0xffff0000, v123
	ds_write_b128 v245, v[134:137] offset:20480
	v_lshlrev_b32_e32 v134, 16, v124
	v_and_b32_e32 v135, 0xffff0000, v124
	s_waitcnt lgkmcnt(6)
	v_pk_fma_f32 v[0:1], v[98:99], v[84:85], v[4:5] op_sel_hi:[0,1,1] neg_lo:[1,0,0] neg_hi:[1,0,0]
	v_pk_fma_f32 v[2:3], v[98:99], v[86:87], v[6:7] op_sel_hi:[0,1,1] neg_lo:[1,0,0] neg_hi:[1,0,0]
	ds_read_b128 v[48:51], v246 offset:7680
	v_pk_mul_f32 v[96:97], v[0:1], v[20:21]
	ds_read_b128 v[52:55], v246 offset:7936
	v_pk_fma_f32 v[96:97], v[2:3], v[22:23], v[96:97]
	v_pk_fma_f32 v[4:5], v[0:1], v[12:13], v[0:1] neg_lo:[1,0,0] neg_hi:[1,0,0]
	v_add_f32_e32 v98, v96, v97
	v_pk_fma_f32 v[6:7], v[2:3], v[14:15], v[2:3] neg_lo:[1,0,0] neg_hi:[1,0,0]
	ds_read_b128 v[56:59], v246 offset:8192
	v_add_f32_dpp v98, v98, v98 quad_perm:[1,0,3,2] row_mask:0xf bank_mask:0xf bound_ctrl:1
	v_pk_fma_f32 v[4:5], v[16:17], v[92:93], v[4:5] op_sel_hi:[1,0,1]
	v_pk_fma_f32 v[6:7], v[18:19], v[92:93], v[6:7] op_sel_hi:[1,0,1]
	v_add_f32_dpp v98, v98, v98 quad_perm:[2,3,0,1] row_mask:0xf bank_mask:0xf bound_ctrl:1
	v_pk_mul_f32 v[100:101], v[0:1], v[68:69]
	v_pk_fma_f32 v[100:101], v[2:3], v[70:71], v[100:101]
	v_add_f32_dpp v98, v98, v98 row_half_mirror row_mask:0xf bank_mask:0xf bound_ctrl:1
	v_add_f32_e32 v105, v100, v101
	v_lshlrev_b32_e32 v136, 16, v125
	v_add_f32_dpp v98, v98, v98 row_mirror row_mask:0xf bank_mask:0xf bound_ctrl:1
	ds_read_b128 v[60:63], v246 offset:8448
	ds_read_b128 v[64:67], v246 offset:8704
	v_add_f32_dpp v106, v102, v102 row_mirror row_mask:0xf bank_mask:0x3 bound_ctrl:1
	v_add_f32_dpp v107, v104, v104 row_mirror row_mask:0xf bank_mask:0x3 bound_ctrl:1
	v_add_f32_dpp v106, v103, v103 row_mirror row_mask:0xf bank_mask:0xc bound_ctrl:1
	v_and_b32_e32 v137, 0xffff0000, v125
	ds_write_b128 v245, v[134:137] offset:20736
	v_lshlrev_b32_e32 v134, 16, v126
	v_and_b32_e32 v135, 0xffff0000, v126
	s_waitcnt lgkmcnt(7)
	v_pk_fma_f32 v[0:1], v[98:99], v[24:25], v[4:5] op_sel_hi:[0,1,1] neg_lo:[1,0,0] neg_hi:[1,0,0]
	v_pk_fma_f32 v[2:3], v[98:99], v[26:27], v[6:7] op_sel_hi:[0,1,1] neg_lo:[1,0,0] neg_hi:[1,0,0]
	ds_read_b128 v[68:71], v246 offset:8960
	v_pk_mul_f32 v[96:97], v[0:1], v[40:41]
	ds_read_b128 v[72:75], v246 offset:9216
	v_pk_fma_f32 v[96:97], v[2:3], v[42:43], v[96:97]
	v_pk_fma_f32 v[4:5], v[0:1], v[32:33], v[0:1] neg_lo:[1,0,0] neg_hi:[1,0,0]
	v_add_f32_e32 v98, v96, v97
	v_pk_fma_f32 v[6:7], v[2:3], v[34:35], v[2:3] neg_lo:[1,0,0] neg_hi:[1,0,0]
	ds_read_b128 v[76:79], v246 offset:9472
	v_add_f32_dpp v98, v98, v98 quad_perm:[1,0,3,2] row_mask:0xf bank_mask:0xf bound_ctrl:1
	v_pk_fma_f32 v[4:5], v[36:37], v[92:93], v[4:5] op_sel:[0,1,0] op_sel_hi:[1,1,1]
	v_pk_fma_f32 v[6:7], v[38:39], v[92:93], v[6:7] op_sel:[0,1,0] op_sel_hi:[1,1,1]
	v_add_f32_dpp v98, v98, v98 quad_perm:[2,3,0,1] row_mask:0xf bank_mask:0xf bound_ctrl:1
	v_pk_mul_f32 v[100:101], v[0:1], v[8:9]
	v_pk_fma_f32 v[100:101], v[2:3], v[10:11], v[100:101]
	v_add_f32_dpp v98, v98, v98 row_half_mirror row_mask:0xf bank_mask:0xf bound_ctrl:1
	v_add_f32_e32 v250, v100, v101
	v_add_f32_dpp v107, v105, v105 row_mirror row_mask:0xf bank_mask:0xc bound_ctrl:1
	v_add_f32_dpp v98, v98, v98 row_mirror row_mask:0xf bank_mask:0xf bound_ctrl:1
	ds_read_b128 v[80:83], v246 offset:9728
	ds_read_b128 v[84:87], v246 offset:9984
	v_add_f32_dpp v108, v106, v106 row_half_mirror row_mask:0xf bank_mask:0x5 bound_ctrl:1
	v_add_f32_dpp v108, v107, v107 row_half_mirror row_mask:0xf bank_mask:0xa bound_ctrl:1
	v_lshlrev_b32_e32 v136, 16, v127
	v_and_b32_e32 v137, 0xffff0000, v127
	ds_write_b128 v245, v[134:137] offset:20992
	v_lshlrev_b32_e32 v134, 16, v128
	s_waitcnt lgkmcnt(7)
	v_pk_fma_f32 v[0:1], v[98:99], v[44:45], v[4:5] op_sel_hi:[0,1,1] neg_lo:[1,0,0] neg_hi:[1,0,0]
	v_pk_fma_f32 v[2:3], v[98:99], v[46:47], v[6:7] op_sel_hi:[0,1,1] neg_lo:[1,0,0] neg_hi:[1,0,0]
	ds_read_b128 v[8:11], v246 offset:10240
	v_pk_mul_f32 v[96:97], v[0:1], v[60:61]
	ds_read_b128 v[12:15], v246 offset:10496
	v_pk_fma_f32 v[96:97], v[2:3], v[62:63], v[96:97]
	v_pk_fma_f32 v[4:5], v[0:1], v[52:53], v[0:1] neg_lo:[1,0,0] neg_hi:[1,0,0]
	v_add_f32_e32 v98, v96, v97
	v_pk_fma_f32 v[6:7], v[2:3], v[54:55], v[2:3] neg_lo:[1,0,0] neg_hi:[1,0,0]
	ds_read_b128 v[16:19], v246 offset:10752
	v_add_f32_dpp v98, v98, v98 quad_perm:[1,0,3,2] row_mask:0xf bank_mask:0xf bound_ctrl:1
	v_pk_fma_f32 v[4:5], v[56:57], v[94:95], v[4:5] op_sel_hi:[1,0,1]
	v_pk_fma_f32 v[6:7], v[58:59], v[94:95], v[6:7] op_sel_hi:[1,0,1]
	v_add_f32_dpp v98, v98, v98 quad_perm:[2,3,0,1] row_mask:0xf bank_mask:0xf bound_ctrl:1
	v_pk_mul_f32 v[100:101], v[0:1], v[28:29]
	v_pk_fma_f32 v[100:101], v[2:3], v[30:31], v[100:101]
	v_add_f32_dpp v98, v98, v98 row_half_mirror row_mask:0xf bank_mask:0xf bound_ctrl:1
	v_add_f32_e32 v251, v100, v101
	v_add_f32_dpp v108, v108, v108 quad_perm:[1,0,3,2] row_mask:0xf bank_mask:0xf bound_ctrl:1
	v_add_f32_dpp v98, v98, v98 row_mirror row_mask:0xf bank_mask:0xf bound_ctrl:1
	ds_read_b128 v[20:23], v246 offset:11008
	ds_read_b128 v[24:27], v246 offset:11264
	ds_read_b128 v[88:91], v247 offset:32
	v_add_f32_dpp v108, v108, v108 quad_perm:[2,3,0,1] row_mask:0xf bank_mask:0xf bound_ctrl:1
	v_cvt_pk_bf16_f32 v109, v108, v108
	global_store_short v249, v109, s[10:11]
	v_and_b32_e32 v135, 0xffff0000, v128
	v_lshlrev_b32_e32 v136, 16, v129
	v_and_b32_e32 v137, 0xffff0000, v129
	ds_write_b128 v245, v[134:137] offset:21248
	s_waitcnt lgkmcnt(8)
	v_pk_fma_f32 v[0:1], v[98:99], v[64:65], v[4:5] op_sel_hi:[0,1,1] neg_lo:[1,0,0] neg_hi:[1,0,0]
	v_pk_fma_f32 v[2:3], v[98:99], v[66:67], v[6:7] op_sel_hi:[0,1,1] neg_lo:[1,0,0] neg_hi:[1,0,0]
	ds_read_b128 v[28:31], v246 offset:11520
	v_pk_mul_f32 v[96:97], v[0:1], v[80:81]
	ds_read_b128 v[32:35], v246 offset:11776
	v_pk_fma_f32 v[96:97], v[2:3], v[82:83], v[96:97]
	v_pk_fma_f32 v[4:5], v[0:1], v[72:73], v[0:1] neg_lo:[1,0,0] neg_hi:[1,0,0]
	v_add_f32_e32 v98, v96, v97
	v_pk_fma_f32 v[6:7], v[2:3], v[74:75], v[2:3] neg_lo:[1,0,0] neg_hi:[1,0,0]
	ds_read_b128 v[36:39], v246 offset:12032
	v_add_f32_dpp v98, v98, v98 quad_perm:[1,0,3,2] row_mask:0xf bank_mask:0xf bound_ctrl:1
	v_pk_fma_f32 v[4:5], v[76:77], v[94:95], v[4:5] op_sel:[0,1,0] op_sel_hi:[1,1,1]
	v_pk_fma_f32 v[6:7], v[78:79], v[94:95], v[6:7] op_sel:[0,1,0] op_sel_hi:[1,1,1]
	v_add_f32_dpp v98, v98, v98 quad_perm:[2,3,0,1] row_mask:0xf bank_mask:0xf bound_ctrl:1
	v_pk_mul_f32 v[100:101], v[0:1], v[48:49]
	v_pk_fma_f32 v[100:101], v[2:3], v[50:51], v[100:101]
	v_add_f32_dpp v98, v98, v98 row_half_mirror row_mask:0xf bank_mask:0xf bound_ctrl:1
	v_add_f32_e32 v252, v100, v101
	s_add_u32 s10, s10, 0x2000
	s_addc_u32 s11, s11, 0
	v_add_f32_dpp v98, v98, v98 row_mirror row_mask:0xf bank_mask:0xf bound_ctrl:1
	ds_read_b128 v[40:43], v246 offset:12288
	ds_read_b128 v[44:47], v246 offset:12544
	v_lshlrev_b32_e32 v134, 16, v130
	v_and_b32_e32 v135, 0xffff0000, v130
	v_lshlrev_b32_e32 v136, 16, v131
	v_and_b32_e32 v137, 0xffff0000, v131
	s_waitcnt lgkmcnt(6)
	v_pk_fma_f32 v[0:1], v[98:99], v[84:85], v[4:5] op_sel_hi:[0,1,1] neg_lo:[1,0,0] neg_hi:[1,0,0]
	v_pk_fma_f32 v[2:3], v[98:99], v[86:87], v[6:7] op_sel_hi:[0,1,1] neg_lo:[1,0,0] neg_hi:[1,0,0]
	ds_read_b128 v[48:51], v246 offset:12800
	v_pk_mul_f32 v[96:97], v[0:1], v[20:21]
	ds_read_b128 v[52:55], v246 offset:13056
	v_pk_fma_f32 v[96:97], v[2:3], v[22:23], v[96:97]
	v_pk_fma_f32 v[4:5], v[0:1], v[12:13], v[0:1] neg_lo:[1,0,0] neg_hi:[1,0,0]
	v_add_f32_e32 v98, v96, v97
	v_pk_fma_f32 v[6:7], v[2:3], v[14:15], v[2:3] neg_lo:[1,0,0] neg_hi:[1,0,0]
	ds_read_b128 v[56:59], v246 offset:13312
	v_add_f32_dpp v98, v98, v98 quad_perm:[1,0,3,2] row_mask:0xf bank_mask:0xf bound_ctrl:1
	v_pk_fma_f32 v[4:5], v[16:17], v[88:89], v[4:5] op_sel_hi:[1,0,1]
	v_pk_fma_f32 v[6:7], v[18:19], v[88:89], v[6:7] op_sel_hi:[1,0,1]
	v_add_f32_dpp v98, v98, v98 quad_perm:[2,3,0,1] row_mask:0xf bank_mask:0xf bound_ctrl:1
	v_pk_mul_f32 v[100:101], v[0:1], v[68:69]
	v_pk_fma_f32 v[100:101], v[2:3], v[70:71], v[100:101]
	v_add_f32_dpp v98, v98, v98 row_half_mirror row_mask:0xf bank_mask:0xf bound_ctrl:1
	v_add_f32_e32 v253, v100, v101
	ds_write_b128 v245, v[134:137] offset:21504
	v_add_f32_dpp v98, v98, v98 row_mirror row_mask:0xf bank_mask:0xf bound_ctrl:1
	ds_read_b128 v[60:63], v246 offset:13568
	ds_read_b128 v[64:67], v246 offset:13824
	v_add_f32_dpp v106, v250, v250 row_mirror row_mask:0xf bank_mask:0x3 bound_ctrl:1
	v_add_f32_dpp v107, v252, v252 row_mirror row_mask:0xf bank_mask:0x3 bound_ctrl:1
	v_add_f32_dpp v106, v251, v251 row_mirror row_mask:0xf bank_mask:0xc bound_ctrl:1
	v_lshlrev_b32_e32 v134, 16, v132
	ds_write_b32 v248, v134 offset:1280
	s_waitcnt lgkmcnt(7)
	v_pk_fma_f32 v[0:1], v[98:99], v[24:25], v[4:5] op_sel_hi:[0,1,1] neg_lo:[1,0,0] neg_hi:[1,0,0]
	v_pk_fma_f32 v[2:3], v[98:99], v[26:27], v[6:7] op_sel_hi:[0,1,1] neg_lo:[1,0,0] neg_hi:[1,0,0]
	ds_read_b128 v[68:71], v246 offset:14080
	v_pk_mul_f32 v[96:97], v[0:1], v[40:41]
	ds_read_b128 v[72:75], v246 offset:14336
	v_pk_fma_f32 v[96:97], v[2:3], v[42:43], v[96:97]
	v_pk_fma_f32 v[4:5], v[0:1], v[32:33], v[0:1] neg_lo:[1,0,0] neg_hi:[1,0,0]
	v_add_f32_e32 v98, v96, v97
	v_pk_fma_f32 v[6:7], v[2:3], v[34:35], v[2:3] neg_lo:[1,0,0] neg_hi:[1,0,0]
	ds_read_b128 v[76:79], v246 offset:14592
	v_add_f32_dpp v98, v98, v98 quad_perm:[1,0,3,2] row_mask:0xf bank_mask:0xf bound_ctrl:1
	v_pk_fma_f32 v[4:5], v[36:37], v[88:89], v[4:5] op_sel:[0,1,0] op_sel_hi:[1,1,1]
	v_pk_fma_f32 v[6:7], v[38:39], v[88:89], v[6:7] op_sel:[0,1,0] op_sel_hi:[1,1,1]
	v_add_f32_dpp v98, v98, v98 quad_perm:[2,3,0,1] row_mask:0xf bank_mask:0xf bound_ctrl:1
	v_pk_mul_f32 v[100:101], v[0:1], v[8:9]
	v_pk_fma_f32 v[100:101], v[2:3], v[10:11], v[100:101]
	v_add_f32_dpp v98, v98, v98 row_half_mirror row_mask:0xf bank_mask:0xf bound_ctrl:1
	v_add_f32_e32 v102, v100, v101
	v_add_f32_dpp v107, v253, v253 row_mirror row_mask:0xf bank_mask:0xc bound_ctrl:1
	v_add_f32_dpp v98, v98, v98 row_mirror row_mask:0xf bank_mask:0xf bound_ctrl:1
	ds_read_b128 v[80:83], v246 offset:14848
	ds_read_b128 v[84:87], v246 offset:15104
	v_add_f32_dpp v108, v106, v106 row_half_mirror row_mask:0xf bank_mask:0x5 bound_ctrl:1
	v_add_f32_dpp v108, v107, v107 row_half_mirror row_mask:0xf bank_mask:0xa bound_ctrl:1
	s_waitcnt lgkmcnt(6)
	v_pk_fma_f32 v[0:1], v[98:99], v[44:45], v[4:5] op_sel_hi:[0,1,1] neg_lo:[1,0,0] neg_hi:[1,0,0]
	v_pk_fma_f32 v[2:3], v[98:99], v[46:47], v[6:7] op_sel_hi:[0,1,1] neg_lo:[1,0,0] neg_hi:[1,0,0]
	ds_read_b128 v[8:11], v246 offset:15360
	v_pk_mul_f32 v[96:97], v[0:1], v[60:61]
	ds_read_b128 v[12:15], v246 offset:15616
	v_pk_fma_f32 v[96:97], v[2:3], v[62:63], v[96:97]
	v_pk_fma_f32 v[4:5], v[0:1], v[52:53], v[0:1] neg_lo:[1,0,0] neg_hi:[1,0,0]
	v_add_f32_e32 v98, v96, v97
	v_pk_fma_f32 v[6:7], v[2:3], v[54:55], v[2:3] neg_lo:[1,0,0] neg_hi:[1,0,0]
	ds_read_b128 v[16:19], v246 offset:15872
	v_add_f32_dpp v98, v98, v98 quad_perm:[1,0,3,2] row_mask:0xf bank_mask:0xf bound_ctrl:1
	v_pk_fma_f32 v[4:5], v[56:57], v[90:91], v[4:5] op_sel_hi:[1,0,1]
	v_pk_fma_f32 v[6:7], v[58:59], v[90:91], v[6:7] op_sel_hi:[1,0,1]
	v_add_f32_dpp v98, v98, v98 quad_perm:[2,3,0,1] row_mask:0xf bank_mask:0xf bound_ctrl:1
	v_pk_mul_f32 v[100:101], v[0:1], v[28:29]
	v_pk_fma_f32 v[100:101], v[2:3], v[30:31], v[100:101]
	v_add_f32_dpp v98, v98, v98 row_half_mirror row_mask:0xf bank_mask:0xf bound_ctrl:1
	v_add_f32_e32 v103, v100, v101
	v_add_f32_dpp v108, v108, v108 quad_perm:[1,0,3,2] row_mask:0xf bank_mask:0xf bound_ctrl:1
	v_add_f32_dpp v98, v98, v98 row_mirror row_mask:0xf bank_mask:0xf bound_ctrl:1
	ds_read_b128 v[20:23], v246 offset:16128
	ds_read_b128 v[24:27], v246 offset:16384
	ds_read_b128 v[92:95], v247 offset:48
	v_add_f32_dpp v108, v108, v108 quad_perm:[2,3,0,1] row_mask:0xf bank_mask:0xf bound_ctrl:1
	v_cvt_pk_bf16_f32 v109, v108, v108
	global_store_short v249, v109, s[10:11]
	s_waitcnt lgkmcnt(6)
	v_pk_fma_f32 v[0:1], v[98:99], v[64:65], v[4:5] op_sel_hi:[0,1,1] neg_lo:[1,0,0] neg_hi:[1,0,0]
	v_pk_fma_f32 v[2:3], v[98:99], v[66:67], v[6:7] op_sel_hi:[0,1,1] neg_lo:[1,0,0] neg_hi:[1,0,0]
	ds_read_b128 v[28:31], v246 offset:16640
	v_pk_mul_f32 v[96:97], v[0:1], v[80:81]
	ds_read_b128 v[32:35], v246 offset:16896
	v_pk_fma_f32 v[96:97], v[2:3], v[82:83], v[96:97]
	v_pk_fma_f32 v[4:5], v[0:1], v[72:73], v[0:1] neg_lo:[1,0,0] neg_hi:[1,0,0]
	v_add_f32_e32 v98, v96, v97
	v_pk_fma_f32 v[6:7], v[2:3], v[74:75], v[2:3] neg_lo:[1,0,0] neg_hi:[1,0,0]
	ds_read_b128 v[36:39], v246 offset:17152
	v_add_f32_dpp v98, v98, v98 quad_perm:[1,0,3,2] row_mask:0xf bank_mask:0xf bound_ctrl:1
	v_pk_fma_f32 v[4:5], v[76:77], v[90:91], v[4:5] op_sel:[0,1,0] op_sel_hi:[1,1,1]
	v_pk_fma_f32 v[6:7], v[78:79], v[90:91], v[6:7] op_sel:[0,1,0] op_sel_hi:[1,1,1]
	v_add_f32_dpp v98, v98, v98 quad_perm:[2,3,0,1] row_mask:0xf bank_mask:0xf bound_ctrl:1
	v_pk_mul_f32 v[100:101], v[0:1], v[48:49]
	v_pk_fma_f32 v[100:101], v[2:3], v[50:51], v[100:101]
	v_add_f32_dpp v98, v98, v98 row_half_mirror row_mask:0xf bank_mask:0xf bound_ctrl:1
	v_add_f32_e32 v104, v100, v101
	s_add_u32 s10, s10, 0x2000
	s_addc_u32 s11, s11, 0
	v_add_f32_dpp v98, v98, v98 row_mirror row_mask:0xf bank_mask:0xf bound_ctrl:1
	ds_read_b128 v[40:43], v246 offset:17408
	ds_read_b128 v[44:47], v246 offset:17664
	s_waitcnt lgkmcnt(5)
	v_pk_fma_f32 v[0:1], v[98:99], v[84:85], v[4:5] op_sel_hi:[0,1,1] neg_lo:[1,0,0] neg_hi:[1,0,0]
	v_pk_fma_f32 v[2:3], v[98:99], v[86:87], v[6:7] op_sel_hi:[0,1,1] neg_lo:[1,0,0] neg_hi:[1,0,0]
	ds_read_b128 v[48:51], v246 offset:17920
	v_pk_mul_f32 v[96:97], v[0:1], v[20:21]
	ds_read_b128 v[52:55], v246 offset:18176
	v_pk_fma_f32 v[96:97], v[2:3], v[22:23], v[96:97]
	v_pk_fma_f32 v[4:5], v[0:1], v[12:13], v[0:1] neg_lo:[1,0,0] neg_hi:[1,0,0]
	v_add_f32_e32 v98, v96, v97
	v_pk_fma_f32 v[6:7], v[2:3], v[14:15], v[2:3] neg_lo:[1,0,0] neg_hi:[1,0,0]
	ds_read_b128 v[56:59], v246 offset:18432
	v_add_f32_dpp v98, v98, v98 quad_perm:[1,0,3,2] row_mask:0xf bank_mask:0xf bound_ctrl:1
	v_pk_fma_f32 v[4:5], v[16:17], v[92:93], v[4:5] op_sel_hi:[1,0,1]
	v_pk_fma_f32 v[6:7], v[18:19], v[92:93], v[6:7] op_sel_hi:[1,0,1]
	v_add_f32_dpp v98, v98, v98 quad_perm:[2,3,0,1] row_mask:0xf bank_mask:0xf bound_ctrl:1
	v_pk_mul_f32 v[100:101], v[0:1], v[68:69]
	v_pk_fma_f32 v[100:101], v[2:3], v[70:71], v[100:101]
	v_add_f32_dpp v98, v98, v98 row_half_mirror row_mask:0xf bank_mask:0xf bound_ctrl:1
	v_add_f32_e32 v105, v100, v101
	ds_read_b128 v[60:63], v246 offset:18688
	v_add_f32_dpp v98, v98, v98 row_mirror row_mask:0xf bank_mask:0xf bound_ctrl:1
	ds_read_b128 v[64:67], v246 offset:18944
	v_add_f32_dpp v106, v102, v102 row_mirror row_mask:0xf bank_mask:0x3 bound_ctrl:1
	v_add_f32_dpp v107, v104, v104 row_mirror row_mask:0xf bank_mask:0x3 bound_ctrl:1
	v_add_f32_dpp v106, v103, v103 row_mirror row_mask:0xf bank_mask:0xc bound_ctrl:1
	s_waitcnt lgkmcnt(5)
	v_pk_fma_f32 v[0:1], v[98:99], v[24:25], v[4:5] op_sel_hi:[0,1,1] neg_lo:[1,0,0] neg_hi:[1,0,0]
	v_pk_fma_f32 v[2:3], v[98:99], v[26:27], v[6:7] op_sel_hi:[0,1,1] neg_lo:[1,0,0] neg_hi:[1,0,0]
	ds_read_b128 v[68:71], v246 offset:19200
	v_pk_mul_f32 v[96:97], v[0:1], v[40:41]
	ds_read_b128 v[72:75], v246 offset:19456
	v_pk_fma_f32 v[96:97], v[2:3], v[42:43], v[96:97]
	v_pk_fma_f32 v[4:5], v[0:1], v[32:33], v[0:1] neg_lo:[1,0,0] neg_hi:[1,0,0]
	v_add_f32_e32 v98, v96, v97
	v_pk_fma_f32 v[6:7], v[2:3], v[34:35], v[2:3] neg_lo:[1,0,0] neg_hi:[1,0,0]
	ds_read_b128 v[76:79], v246 offset:19712
	v_add_f32_dpp v98, v98, v98 quad_perm:[1,0,3,2] row_mask:0xf bank_mask:0xf bound_ctrl:1
	v_pk_fma_f32 v[4:5], v[36:37], v[92:93], v[4:5] op_sel:[0,1,0] op_sel_hi:[1,1,1]
	v_pk_fma_f32 v[6:7], v[38:39], v[92:93], v[6:7] op_sel:[0,1,0] op_sel_hi:[1,1,1]
	v_add_f32_dpp v98, v98, v98 quad_perm:[2,3,0,1] row_mask:0xf bank_mask:0xf bound_ctrl:1
	v_pk_mul_f32 v[100:101], v[0:1], v[8:9]
	v_pk_fma_f32 v[100:101], v[2:3], v[10:11], v[100:101]
	v_add_f32_dpp v98, v98, v98 row_half_mirror row_mask:0xf bank_mask:0xf bound_ctrl:1
	v_add_f32_e32 v250, v100, v101
	v_add_f32_dpp v107, v105, v105 row_mirror row_mask:0xf bank_mask:0xc bound_ctrl:1
	v_add_f32_dpp v98, v98, v98 row_mirror row_mask:0xf bank_mask:0xf bound_ctrl:1
	ds_read_b128 v[80:83], v246 offset:19968
	ds_read_b128 v[84:87], v246 offset:20224
	v_add_f32_dpp v108, v106, v106 row_half_mirror row_mask:0xf bank_mask:0x5 bound_ctrl:1
	v_add_f32_dpp v108, v107, v107 row_half_mirror row_mask:0xf bank_mask:0xa bound_ctrl:1
	s_waitcnt lgkmcnt(15)
	s_barrier
	s_waitcnt lgkmcnt(5)
	v_pk_fma_f32 v[0:1], v[98:99], v[44:45], v[4:5] op_sel_hi:[0,1,1] neg_lo:[1,0,0] neg_hi:[1,0,0]
	v_pk_fma_f32 v[2:3], v[98:99], v[46:47], v[6:7] op_sel_hi:[0,1,1] neg_lo:[1,0,0] neg_hi:[1,0,0]
	ds_read_b128 v[8:11], v246 offset:20480
	v_pk_mul_f32 v[96:97], v[0:1], v[60:61]
	ds_read_b128 v[12:15], v246 offset:20736
	v_pk_fma_f32 v[96:97], v[2:3], v[62:63], v[96:97]
	v_pk_fma_f32 v[4:5], v[0:1], v[52:53], v[0:1] neg_lo:[1,0,0] neg_hi:[1,0,0]
	v_add_f32_e32 v98, v96, v97
	v_pk_fma_f32 v[6:7], v[2:3], v[54:55], v[2:3] neg_lo:[1,0,0] neg_hi:[1,0,0]
	ds_read_b128 v[16:19], v246 offset:20992
	v_add_f32_dpp v98, v98, v98 quad_perm:[1,0,3,2] row_mask:0xf bank_mask:0xf bound_ctrl:1
	v_pk_fma_f32 v[4:5], v[56:57], v[94:95], v[4:5] op_sel_hi:[1,0,1]
	v_pk_fma_f32 v[6:7], v[58:59], v[94:95], v[6:7] op_sel_hi:[1,0,1]
	v_add_f32_dpp v98, v98, v98 quad_perm:[2,3,0,1] row_mask:0xf bank_mask:0xf bound_ctrl:1
	v_pk_mul_f32 v[100:101], v[0:1], v[28:29]
	v_pk_fma_f32 v[100:101], v[2:3], v[30:31], v[100:101]
	v_add_f32_dpp v98, v98, v98 row_half_mirror row_mask:0xf bank_mask:0xf bound_ctrl:1
	v_add_f32_e32 v251, v100, v101
	v_add_f32_dpp v108, v108, v108 quad_perm:[1,0,3,2] row_mask:0xf bank_mask:0xf bound_ctrl:1
	v_add_f32_dpp v98, v98, v98 row_mirror row_mask:0xf bank_mask:0xf bound_ctrl:1
	ds_read_b128 v[20:23], v246 offset:21248
	ds_read_b128 v[24:27], v246 offset:21504
	ds_read_b128 v[88:91], v247 offset:1280
	v_add_f32_dpp v108, v108, v108 quad_perm:[2,3,0,1] row_mask:0xf bank_mask:0xf bound_ctrl:1
	v_cvt_pk_bf16_f32 v109, v108, v108
	global_store_short v249, v109, s[10:11]
	s_waitcnt lgkmcnt(6)
	v_pk_fma_f32 v[0:1], v[98:99], v[64:65], v[4:5] op_sel_hi:[0,1,1] neg_lo:[1,0,0] neg_hi:[1,0,0]
	v_pk_fma_f32 v[2:3], v[98:99], v[66:67], v[6:7] op_sel_hi:[0,1,1] neg_lo:[1,0,0] neg_hi:[1,0,0]
	ds_read_b128 v[28:31], v246 offset:21760
	v_pk_mul_f32 v[96:97], v[0:1], v[80:81]
	ds_read_b128 v[32:35], v246 offset:22016
	v_pk_fma_f32 v[96:97], v[2:3], v[82:83], v[96:97]
	v_pk_fma_f32 v[4:5], v[0:1], v[72:73], v[0:1] neg_lo:[1,0,0] neg_hi:[1,0,0]
	v_add_f32_e32 v98, v96, v97
	v_pk_fma_f32 v[6:7], v[2:3], v[74:75], v[2:3] neg_lo:[1,0,0] neg_hi:[1,0,0]
	ds_read_b128 v[36:39], v246 offset:22272
	v_add_f32_dpp v98, v98, v98 quad_perm:[1,0,3,2] row_mask:0xf bank_mask:0xf bound_ctrl:1
	v_pk_fma_f32 v[4:5], v[76:77], v[94:95], v[4:5] op_sel:[0,1,0] op_sel_hi:[1,1,1]
	v_pk_fma_f32 v[6:7], v[78:79], v[94:95], v[6:7] op_sel:[0,1,0] op_sel_hi:[1,1,1]
	v_add_f32_dpp v98, v98, v98 quad_perm:[2,3,0,1] row_mask:0xf bank_mask:0xf bound_ctrl:1
	v_pk_mul_f32 v[100:101], v[0:1], v[48:49]
	v_pk_fma_f32 v[100:101], v[2:3], v[50:51], v[100:101]
	v_add_f32_dpp v98, v98, v98 row_half_mirror row_mask:0xf bank_mask:0xf bound_ctrl:1
	v_add_f32_e32 v252, v100, v101
	s_add_u32 s10, s10, 0x2000
	s_addc_u32 s11, s11, 0
	v_add_f32_dpp v98, v98, v98 row_mirror row_mask:0xf bank_mask:0xf bound_ctrl:1
	ds_read_b128 v[40:43], v246 offset:22528
	ds_read_b128 v[44:47], v246 offset:22784
	s_waitcnt lgkmcnt(5)
	v_pk_fma_f32 v[0:1], v[98:99], v[84:85], v[4:5] op_sel_hi:[0,1,1] neg_lo:[1,0,0] neg_hi:[1,0,0]
	v_pk_fma_f32 v[2:3], v[98:99], v[86:87], v[6:7] op_sel_hi:[0,1,1] neg_lo:[1,0,0] neg_hi:[1,0,0]
	ds_read_b128 v[48:51], v246 offset:23040
	v_pk_mul_f32 v[96:97], v[0:1], v[20:21]
	ds_read_b128 v[52:55], v246 offset:23296
	v_pk_fma_f32 v[96:97], v[2:3], v[22:23], v[96:97]
	v_pk_fma_f32 v[4:5], v[0:1], v[12:13], v[0:1] neg_lo:[1,0,0] neg_hi:[1,0,0]
	v_add_f32_e32 v98, v96, v97
	v_pk_fma_f32 v[6:7], v[2:3], v[14:15], v[2:3] neg_lo:[1,0,0] neg_hi:[1,0,0]
	ds_read_b128 v[56:59], v246 offset:23552
	v_add_f32_dpp v98, v98, v98 quad_perm:[1,0,3,2] row_mask:0xf bank_mask:0xf bound_ctrl:1
	v_pk_fma_f32 v[4:5], v[16:17], v[88:89], v[4:5] op_sel_hi:[1,0,1]
	v_pk_fma_f32 v[6:7], v[18:19], v[88:89], v[6:7] op_sel_hi:[1,0,1]
	v_add_f32_dpp v98, v98, v98 quad_perm:[2,3,0,1] row_mask:0xf bank_mask:0xf bound_ctrl:1
	v_pk_mul_f32 v[100:101], v[0:1], v[68:69]
	v_pk_fma_f32 v[100:101], v[2:3], v[70:71], v[100:101]
	v_add_f32_dpp v98, v98, v98 row_half_mirror row_mask:0xf bank_mask:0xf bound_ctrl:1
	v_add_f32_e32 v253, v100, v101
	ds_read_b128 v[60:63], v246 offset:23808
	v_add_f32_dpp v98, v98, v98 row_mirror row_mask:0xf bank_mask:0xf bound_ctrl:1
	ds_read_b128 v[64:67], v246 offset:24064
	v_add_f32_dpp v106, v250, v250 row_mirror row_mask:0xf bank_mask:0x3 bound_ctrl:1
	v_add_f32_dpp v107, v252, v252 row_mirror row_mask:0xf bank_mask:0x3 bound_ctrl:1
	v_add_f32_dpp v106, v251, v251 row_mirror row_mask:0xf bank_mask:0xc bound_ctrl:1
	s_waitcnt lgkmcnt(5)
	v_pk_fma_f32 v[0:1], v[98:99], v[24:25], v[4:5] op_sel_hi:[0,1,1] neg_lo:[1,0,0] neg_hi:[1,0,0]
	v_pk_fma_f32 v[2:3], v[98:99], v[26:27], v[6:7] op_sel_hi:[0,1,1] neg_lo:[1,0,0] neg_hi:[1,0,0]
	ds_read_b128 v[68:71], v246 offset:24320
	v_pk_mul_f32 v[96:97], v[0:1], v[40:41]
	ds_read_b128 v[72:75], v246 offset:24576
	v_pk_fma_f32 v[96:97], v[2:3], v[42:43], v[96:97]
	v_pk_fma_f32 v[4:5], v[0:1], v[32:33], v[0:1] neg_lo:[1,0,0] neg_hi:[1,0,0]
	v_add_f32_e32 v98, v96, v97
	v_pk_fma_f32 v[6:7], v[2:3], v[34:35], v[2:3] neg_lo:[1,0,0] neg_hi:[1,0,0]
	ds_read_b128 v[76:79], v246 offset:24832
	v_add_f32_dpp v98, v98, v98 quad_perm:[1,0,3,2] row_mask:0xf bank_mask:0xf bound_ctrl:1
	v_pk_fma_f32 v[4:5], v[36:37], v[88:89], v[4:5] op_sel:[0,1,0] op_sel_hi:[1,1,1]
	v_pk_fma_f32 v[6:7], v[38:39], v[88:89], v[6:7] op_sel:[0,1,0] op_sel_hi:[1,1,1]
	v_add_f32_dpp v98, v98, v98 quad_perm:[2,3,0,1] row_mask:0xf bank_mask:0xf bound_ctrl:1
	v_pk_mul_f32 v[100:101], v[0:1], v[8:9]
	v_pk_fma_f32 v[100:101], v[2:3], v[10:11], v[100:101]
	v_add_f32_dpp v98, v98, v98 row_half_mirror row_mask:0xf bank_mask:0xf bound_ctrl:1
	v_add_f32_e32 v102, v100, v101
	v_add_f32_dpp v107, v253, v253 row_mirror row_mask:0xf bank_mask:0xc bound_ctrl:1
	v_add_f32_dpp v98, v98, v98 row_mirror row_mask:0xf bank_mask:0xf bound_ctrl:1
	ds_read_b128 v[80:83], v246 offset:25088
	ds_read_b128 v[84:87], v246 offset:25344
	v_add_f32_dpp v108, v106, v106 row_half_mirror row_mask:0xf bank_mask:0x5 bound_ctrl:1
	v_add_f32_dpp v108, v107, v107 row_half_mirror row_mask:0xf bank_mask:0xa bound_ctrl:1
	s_add_u32 s14, s14, 0x8000
	s_addc_u32 s15, s15, 0
	global_load_dwordx2 v[122:123], v138, s[14:15]
	global_load_dwordx2 v[124:125], v139, s[14:15]
	global_load_dwordx2 v[126:127], v140, s[14:15]
	s_waitcnt lgkmcnt(5)
	v_pk_fma_f32 v[0:1], v[98:99], v[44:45], v[4:5] op_sel_hi:[0,1,1] neg_lo:[1,0,0] neg_hi:[1,0,0]
	v_pk_fma_f32 v[2:3], v[98:99], v[46:47], v[6:7] op_sel_hi:[0,1,1] neg_lo:[1,0,0] neg_hi:[1,0,0]
	ds_read_b128 v[8:11], v246 offset:25600
	v_pk_mul_f32 v[96:97], v[0:1], v[60:61]
	ds_read_b128 v[12:15], v246 offset:25856
	v_pk_fma_f32 v[96:97], v[2:3], v[62:63], v[96:97]
	v_pk_fma_f32 v[4:5], v[0:1], v[52:53], v[0:1] neg_lo:[1,0,0] neg_hi:[1,0,0]
	v_add_f32_e32 v98, v96, v97
	v_pk_fma_f32 v[6:7], v[2:3], v[54:55], v[2:3] neg_lo:[1,0,0] neg_hi:[1,0,0]
	ds_read_b128 v[16:19], v246 offset:26112
	v_add_f32_dpp v98, v98, v98 quad_perm:[1,0,3,2] row_mask:0xf bank_mask:0xf bound_ctrl:1
	v_pk_fma_f32 v[4:5], v[56:57], v[90:91], v[4:5] op_sel_hi:[1,0,1]
	v_pk_fma_f32 v[6:7], v[58:59], v[90:91], v[6:7] op_sel_hi:[1,0,1]
	v_add_f32_dpp v98, v98, v98 quad_perm:[2,3,0,1] row_mask:0xf bank_mask:0xf bound_ctrl:1
	v_pk_mul_f32 v[100:101], v[0:1], v[28:29]
	v_pk_fma_f32 v[100:101], v[2:3], v[30:31], v[100:101]
	v_add_f32_dpp v98, v98, v98 row_half_mirror row_mask:0xf bank_mask:0xf bound_ctrl:1
	v_add_f32_e32 v103, v100, v101
	v_add_f32_dpp v108, v108, v108 quad_perm:[1,0,3,2] row_mask:0xf bank_mask:0xf bound_ctrl:1
	v_add_f32_dpp v98, v98, v98 row_mirror row_mask:0xf bank_mask:0xf bound_ctrl:1
	ds_read_b128 v[20:23], v246 offset:26368
	ds_read_b128 v[24:27], v246 offset:26624
	ds_read_b128 v[92:95], v247 offset:1296
	v_add_f32_dpp v108, v108, v108 quad_perm:[2,3,0,1] row_mask:0xf bank_mask:0xf bound_ctrl:1
	v_cvt_pk_bf16_f32 v109, v108, v108
	global_store_short v249, v109, s[10:11]
	global_load_dwordx2 v[128:129], v141, s[14:15]
	global_load_dwordx2 v[130:131], v243, s[14:15]
	global_load_ushort v132, v244, s[14:15]
	s_waitcnt vmcnt(10)
	s_waitcnt lgkmcnt(6)
	v_pk_fma_f32 v[0:1], v[98:99], v[64:65], v[4:5] op_sel_hi:[0,1,1] neg_lo:[1,0,0] neg_hi:[1,0,0]
	v_pk_fma_f32 v[2:3], v[98:99], v[66:67], v[6:7] op_sel_hi:[0,1,1] neg_lo:[1,0,0] neg_hi:[1,0,0]
	ds_read_b128 v[28:31], v246 offset:26880
	v_pk_mul_f32 v[96:97], v[0:1], v[80:81]
	ds_read_b128 v[32:35], v246 offset:27136
	v_pk_fma_f32 v[96:97], v[2:3], v[82:83], v[96:97]
	v_pk_fma_f32 v[4:5], v[0:1], v[72:73], v[0:1] neg_lo:[1,0,0] neg_hi:[1,0,0]
	v_add_f32_e32 v98, v96, v97
	v_pk_fma_f32 v[6:7], v[2:3], v[74:75], v[2:3] neg_lo:[1,0,0] neg_hi:[1,0,0]
	ds_read_b128 v[36:39], v246 offset:27392
	v_add_f32_dpp v98, v98, v98 quad_perm:[1,0,3,2] row_mask:0xf bank_mask:0xf bound_ctrl:1
	v_pk_fma_f32 v[4:5], v[76:77], v[90:91], v[4:5] op_sel:[0,1,0] op_sel_hi:[1,1,1]
	v_pk_fma_f32 v[6:7], v[78:79], v[90:91], v[6:7] op_sel:[0,1,0] op_sel_hi:[1,1,1]
	v_add_f32_dpp v98, v98, v98 quad_perm:[2,3,0,1] row_mask:0xf bank_mask:0xf bound_ctrl:1
	v_pk_mul_f32 v[100:101], v[0:1], v[48:49]
	v_pk_fma_f32 v[100:101], v[2:3], v[50:51], v[100:101]
	v_add_f32_dpp v98, v98, v98 row_half_mirror row_mask:0xf bank_mask:0xf bound_ctrl:1
	v_add_f32_e32 v104, v100, v101
	s_add_u32 s10, s10, 0x2000
	s_addc_u32 s11, s11, 0
	v_add_f32_dpp v98, v98, v98 row_mirror row_mask:0xf bank_mask:0xf bound_ctrl:1
	ds_read_b128 v[40:43], v246 offset:27648
	ds_read_b128 v[44:47], v246 offset:27904
	v_lshlrev_b32_e32 v134, 16, v110
	v_and_b32_e32 v135, 0xffff0000, v110
	v_lshlrev_b32_e32 v136, 16, v111
	v_and_b32_e32 v137, 0xffff0000, v111
	s_waitcnt lgkmcnt(5)
	v_pk_fma_f32 v[0:1], v[98:99], v[84:85], v[4:5] op_sel_hi:[0,1,1] neg_lo:[1,0,0] neg_hi:[1,0,0]
	v_pk_fma_f32 v[2:3], v[98:99], v[86:87], v[6:7] op_sel_hi:[0,1,1] neg_lo:[1,0,0] neg_hi:[1,0,0]
	ds_read_b128 v[48:51], v246 offset:28160
	v_pk_mul_f32 v[96:97], v[0:1], v[20:21]
	ds_read_b128 v[52:55], v246 offset:28416
	v_pk_fma_f32 v[96:97], v[2:3], v[22:23], v[96:97]
	v_pk_fma_f32 v[4:5], v[0:1], v[12:13], v[0:1] neg_lo:[1,0,0] neg_hi:[1,0,0]
	v_add_f32_e32 v98, v96, v97
	v_pk_fma_f32 v[6:7], v[2:3], v[14:15], v[2:3] neg_lo:[1,0,0] neg_hi:[1,0,0]
	ds_read_b128 v[56:59], v246 offset:28672
	v_add_f32_dpp v98, v98, v98 quad_perm:[1,0,3,2] row_mask:0xf bank_mask:0xf bound_ctrl:1
	v_pk_fma_f32 v[4:5], v[16:17], v[92:93], v[4:5] op_sel_hi:[1,0,1]
	v_pk_fma_f32 v[6:7], v[18:19], v[92:93], v[6:7] op_sel_hi:[1,0,1]
	v_add_f32_dpp v98, v98, v98 quad_perm:[2,3,0,1] row_mask:0xf bank_mask:0xf bound_ctrl:1
	v_pk_mul_f32 v[100:101], v[0:1], v[68:69]
	v_pk_fma_f32 v[100:101], v[2:3], v[70:71], v[100:101]
	v_add_f32_dpp v98, v98, v98 row_half_mirror row_mask:0xf bank_mask:0xf bound_ctrl:1
	v_add_f32_e32 v105, v100, v101
	ds_write_b128 v245, v[134:137] offset:0
	v_add_f32_dpp v98, v98, v98 row_mirror row_mask:0xf bank_mask:0xf bound_ctrl:1
	ds_read_b128 v[60:63], v246 offset:28928
	ds_read_b128 v[64:67], v246 offset:29184
	v_add_f32_dpp v106, v102, v102 row_mirror row_mask:0xf bank_mask:0x3 bound_ctrl:1
	v_add_f32_dpp v107, v104, v104 row_mirror row_mask:0xf bank_mask:0x3 bound_ctrl:1
	v_add_f32_dpp v106, v103, v103 row_mirror row_mask:0xf bank_mask:0xc bound_ctrl:1
	v_lshlrev_b32_e32 v134, 16, v112
	v_and_b32_e32 v135, 0xffff0000, v112
	v_lshlrev_b32_e32 v136, 16, v113
	v_and_b32_e32 v137, 0xffff0000, v113
	s_waitcnt lgkmcnt(6)
	v_pk_fma_f32 v[0:1], v[98:99], v[24:25], v[4:5] op_sel_hi:[0,1,1] neg_lo:[1,0,0] neg_hi:[1,0,0]
	v_pk_fma_f32 v[2:3], v[98:99], v[26:27], v[6:7] op_sel_hi:[0,1,1] neg_lo:[1,0,0] neg_hi:[1,0,0]
	ds_read_b128 v[68:71], v246 offset:29440
	v_pk_mul_f32 v[96:97], v[0:1], v[40:41]
	ds_read_b128 v[72:75], v246 offset:29696
	v_pk_fma_f32 v[96:97], v[2:3], v[42:43], v[96:97]
	v_pk_fma_f32 v[4:5], v[0:1], v[32:33], v[0:1] neg_lo:[1,0,0] neg_hi:[1,0,0]
	v_add_f32_e32 v98, v96, v97
	v_pk_fma_f32 v[6:7], v[2:3], v[34:35], v[2:3] neg_lo:[1,0,0] neg_hi:[1,0,0]
	ds_read_b128 v[76:79], v246 offset:29952
	v_add_f32_dpp v98, v98, v98 quad_perm:[1,0,3,2] row_mask:0xf bank_mask:0xf bound_ctrl:1
	v_pk_fma_f32 v[4:5], v[36:37], v[92:93], v[4:5] op_sel:[0,1,0] op_sel_hi:[1,1,1]
	v_pk_fma_f32 v[6:7], v[38:39], v[92:93], v[6:7] op_sel:[0,1,0] op_sel_hi:[1,1,1]
	v_add_f32_dpp v98, v98, v98 quad_perm:[2,3,0,1] row_mask:0xf bank_mask:0xf bound_ctrl:1
	v_pk_mul_f32 v[100:101], v[0:1], v[8:9]
	v_pk_fma_f32 v[100:101], v[2:3], v[10:11], v[100:101]
	v_add_f32_dpp v98, v98, v98 row_half_mirror row_mask:0xf bank_mask:0xf bound_ctrl:1
	v_add_f32_e32 v250, v100, v101
	v_add_f32_dpp v107, v105, v105 row_mirror row_mask:0xf bank_mask:0xc bound_ctrl:1
	v_add_f32_dpp v98, v98, v98 row_mirror row_mask:0xf bank_mask:0xf bound_ctrl:1
	ds_read_b128 v[80:83], v246 offset:30208
	ds_read_b128 v[84:87], v246 offset:30464
	v_add_f32_dpp v108, v106, v106 row_half_mirror row_mask:0xf bank_mask:0x5 bound_ctrl:1
	v_add_f32_dpp v108, v107, v107 row_half_mirror row_mask:0xf bank_mask:0xa bound_ctrl:1
	ds_write_b128 v245, v[134:137] offset:256
	v_lshlrev_b32_e32 v134, 16, v114
	v_and_b32_e32 v135, 0xffff0000, v114
	v_lshlrev_b32_e32 v136, 16, v115
	s_waitcnt lgkmcnt(6)
	v_pk_fma_f32 v[0:1], v[98:99], v[44:45], v[4:5] op_sel_hi:[0,1,1] neg_lo:[1,0,0] neg_hi:[1,0,0]
	v_pk_fma_f32 v[2:3], v[98:99], v[46:47], v[6:7] op_sel_hi:[0,1,1] neg_lo:[1,0,0] neg_hi:[1,0,0]
	ds_read_b128 v[8:11], v246 offset:30720
	v_pk_mul_f32 v[96:97], v[0:1], v[60:61]
	ds_read_b128 v[12:15], v246 offset:30976
	v_pk_fma_f32 v[96:97], v[2:3], v[62:63], v[96:97]
	v_pk_fma_f32 v[4:5], v[0:1], v[52:53], v[0:1] neg_lo:[1,0,0] neg_hi:[1,0,0]
	v_add_f32_e32 v98, v96, v97
	v_pk_fma_f32 v[6:7], v[2:3], v[54:55], v[2:3] neg_lo:[1,0,0] neg_hi:[1,0,0]
	ds_read_b128 v[16:19], v246 offset:31232
	v_add_f32_dpp v98, v98, v98 quad_perm:[1,0,3,2] row_mask:0xf bank_mask:0xf bound_ctrl:1
	v_pk_fma_f32 v[4:5], v[56:57], v[94:95], v[4:5] op_sel_hi:[1,0,1]
	v_pk_fma_f32 v[6:7], v[58:59], v[94:95], v[6:7] op_sel_hi:[1,0,1]
	v_add_f32_dpp v98, v98, v98 quad_perm:[2,3,0,1] row_mask:0xf bank_mask:0xf bound_ctrl:1
	v_pk_mul_f32 v[100:101], v[0:1], v[28:29]
	v_pk_fma_f32 v[100:101], v[2:3], v[30:31], v[100:101]
	v_add_f32_dpp v98, v98, v98 row_half_mirror row_mask:0xf bank_mask:0xf bound_ctrl:1
	v_add_f32_e32 v251, v100, v101
	v_add_f32_dpp v108, v108, v108 quad_perm:[1,0,3,2] row_mask:0xf bank_mask:0xf bound_ctrl:1
	v_add_f32_dpp v98, v98, v98 row_mirror row_mask:0xf bank_mask:0xf bound_ctrl:1
	ds_read_b128 v[20:23], v246 offset:31488
	ds_read_b128 v[24:27], v246 offset:31744
	ds_read_b128 v[88:91], v247 offset:1312
	v_add_f32_dpp v108, v108, v108 quad_perm:[2,3,0,1] row_mask:0xf bank_mask:0xf bound_ctrl:1
	v_cvt_pk_bf16_f32 v109, v108, v108
	global_store_short v249, v109, s[10:11]
	v_and_b32_e32 v137, 0xffff0000, v115
	ds_write_b128 v245, v[134:137] offset:512
	v_lshlrev_b32_e32 v134, 16, v116
	v_and_b32_e32 v135, 0xffff0000, v116
	s_waitcnt lgkmcnt(8)
	v_pk_fma_f32 v[0:1], v[98:99], v[64:65], v[4:5] op_sel_hi:[0,1,1] neg_lo:[1,0,0] neg_hi:[1,0,0]
	v_pk_fma_f32 v[2:3], v[98:99], v[66:67], v[6:7] op_sel_hi:[0,1,1] neg_lo:[1,0,0] neg_hi:[1,0,0]
	ds_read_b128 v[28:31], v246 offset:32000
	v_pk_mul_f32 v[96:97], v[0:1], v[80:81]
	ds_read_b128 v[32:35], v246 offset:32256
	v_pk_fma_f32 v[96:97], v[2:3], v[82:83], v[96:97]
	v_pk_fma_f32 v[4:5], v[0:1], v[72:73], v[0:1] neg_lo:[1,0,0] neg_hi:[1,0,0]
	v_add_f32_e32 v98, v96, v97
	v_pk_fma_f32 v[6:7], v[2:3], v[74:75], v[2:3] neg_lo:[1,0,0] neg_hi:[1,0,0]
	ds_read_b128 v[36:39], v246 offset:32512
	v_add_f32_dpp v98, v98, v98 quad_perm:[1,0,3,2] row_mask:0xf bank_mask:0xf bound_ctrl:1
	v_pk_fma_f32 v[4:5], v[76:77], v[94:95], v[4:5] op_sel:[0,1,0] op_sel_hi:[1,1,1]
	v_pk_fma_f32 v[6:7], v[78:79], v[94:95], v[6:7] op_sel:[0,1,0] op_sel_hi:[1,1,1]
	v_add_f32_dpp v98, v98, v98 quad_perm:[2,3,0,1] row_mask:0xf bank_mask:0xf bound_ctrl:1
	v_pk_mul_f32 v[100:101], v[0:1], v[48:49]
	v_pk_fma_f32 v[100:101], v[2:3], v[50:51], v[100:101]
	v_add_f32_dpp v98, v98, v98 row_half_mirror row_mask:0xf bank_mask:0xf bound_ctrl:1
	v_add_f32_e32 v252, v100, v101
	s_add_u32 s10, s10, 0x2000
	s_addc_u32 s11, s11, 0
	v_add_f32_dpp v98, v98, v98 row_mirror row_mask:0xf bank_mask:0xf bound_ctrl:1
	ds_read_b128 v[40:43], v246 offset:32768
	ds_read_b128 v[44:47], v246 offset:33024
	v_lshlrev_b32_e32 v136, 16, v117
	v_and_b32_e32 v137, 0xffff0000, v117
	ds_write_b128 v245, v[134:137] offset:768
	v_lshlrev_b32_e32 v134, 16, v118
	s_waitcnt lgkmcnt(7)
	v_pk_fma_f32 v[0:1], v[98:99], v[84:85], v[4:5] op_sel_hi:[0,1,1] neg_lo:[1,0,0] neg_hi:[1,0,0]
	v_pk_fma_f32 v[2:3], v[98:99], v[86:87], v[6:7] op_sel_hi:[0,1,1] neg_lo:[1,0,0] neg_hi:[1,0,0]
	ds_read_b128 v[48:51], v246 offset:33280
	v_pk_mul_f32 v[96:97], v[0:1], v[20:21]
	ds_read_b128 v[52:55], v246 offset:33536
	v_pk_fma_f32 v[96:97], v[2:3], v[22:23], v[96:97]
	v_pk_fma_f32 v[4:5], v[0:1], v[12:13], v[0:1] neg_lo:[1,0,0] neg_hi:[1,0,0]
	v_add_f32_e32 v98, v96, v97
	v_pk_fma_f32 v[6:7], v[2:3], v[14:15], v[2:3] neg_lo:[1,0,0] neg_hi:[1,0,0]
	ds_read_b128 v[56:59], v246 offset:33792
	v_add_f32_dpp v98, v98, v98 quad_perm:[1,0,3,2] row_mask:0xf bank_mask:0xf bound_ctrl:1
	v_pk_fma_f32 v[4:5], v[16:17], v[88:89], v[4:5] op_sel_hi:[1,0,1]
	v_pk_fma_f32 v[6:7], v[18:19], v[88:89], v[6:7] op_sel_hi:[1,0,1]
	v_add_f32_dpp v98, v98, v98 quad_perm:[2,3,0,1] row_mask:0xf bank_mask:0xf bound_ctrl:1
	v_pk_mul_f32 v[100:101], v[0:1], v[68:69]
	v_pk_fma_f32 v[100:101], v[2:3], v[70:71], v[100:101]
	v_add_f32_dpp v98, v98, v98 row_half_mirror row_mask:0xf bank_mask:0xf bound_ctrl:1
	v_add_f32_e32 v253, v100, v101
	v_and_b32_e32 v135, 0xffff0000, v118
	v_add_f32_dpp v98, v98, v98 row_mirror row_mask:0xf bank_mask:0xf bound_ctrl:1
	ds_read_b128 v[60:63], v246 offset:34048
	ds_read_b128 v[64:67], v246 offset:34304
	v_add_f32_dpp v106, v250, v250 row_mirror row_mask:0xf bank_mask:0x3 bound_ctrl:1
	v_add_f32_dpp v107, v252, v252 row_mirror row_mask:0xf bank_mask:0x3 bound_ctrl:1
	v_add_f32_dpp v106, v251, v251 row_mirror row_mask:0xf bank_mask:0xc bound_ctrl:1
	v_lshlrev_b32_e32 v136, 16, v119
	v_and_b32_e32 v137, 0xffff0000, v119
	ds_write_b128 v245, v[134:137] offset:1024
	v_lshlrev_b32_e32 v134, 16, v120
	s_waitcnt lgkmcnt(7)
	v_pk_fma_f32 v[0:1], v[98:99], v[24:25], v[4:5] op_sel_hi:[0,1,1] neg_lo:[1,0,0] neg_hi:[1,0,0]
	v_pk_fma_f32 v[2:3], v[98:99], v[26:27], v[6:7] op_sel_hi:[0,1,1] neg_lo:[1,0,0] neg_hi:[1,0,0]
	ds_read_b128 v[68:71], v246 offset:34560
	v_pk_mul_f32 v[96:97], v[0:1], v[40:41]
	ds_read_b128 v[72:75], v246 offset:34816
	v_pk_fma_f32 v[96:97], v[2:3], v[42:43], v[96:97]
	v_pk_fma_f32 v[4:5], v[0:1], v[32:33], v[0:1] neg_lo:[1,0,0] neg_hi:[1,0,0]
	v_add_f32_e32 v98, v96, v97
	v_pk_fma_f32 v[6:7], v[2:3], v[34:35], v[2:3] neg_lo:[1,0,0] neg_hi:[1,0,0]
	ds_read_b128 v[76:79], v246 offset:35072
	v_add_f32_dpp v98, v98, v98 quad_perm:[1,0,3,2] row_mask:0xf bank_mask:0xf bound_ctrl:1
	v_pk_fma_f32 v[4:5], v[36:37], v[88:89], v[4:5] op_sel:[0,1,0] op_sel_hi:[1,1,1]
	v_pk_fma_f32 v[6:7], v[38:39], v[88:89], v[6:7] op_sel:[0,1,0] op_sel_hi:[1,1,1]
	v_add_f32_dpp v98, v98, v98 quad_perm:[2,3,0,1] row_mask:0xf bank_mask:0xf bound_ctrl:1
	v_pk_mul_f32 v[100:101], v[0:1], v[8:9]
	v_pk_fma_f32 v[100:101], v[2:3], v[10:11], v[100:101]
	v_add_f32_dpp v98, v98, v98 row_half_mirror row_mask:0xf bank_mask:0xf bound_ctrl:1
	v_add_f32_e32 v102, v100, v101
	v_add_f32_dpp v107, v253, v253 row_mirror row_mask:0xf bank_mask:0xc bound_ctrl:1
	v_add_f32_dpp v98, v98, v98 row_mirror row_mask:0xf bank_mask:0xf bound_ctrl:1
	ds_read_b128 v[80:83], v246 offset:35328
	ds_read_b128 v[84:87], v246 offset:35584
	v_add_f32_dpp v108, v106, v106 row_half_mirror row_mask:0xf bank_mask:0x5 bound_ctrl:1
	v_add_f32_dpp v108, v107, v107 row_half_mirror row_mask:0xf bank_mask:0xa bound_ctrl:1
	ds_write_b32 v248, v134 offset:0
	s_waitcnt lgkmcnt(7)
	v_pk_fma_f32 v[0:1], v[98:99], v[44:45], v[4:5] op_sel_hi:[0,1,1] neg_lo:[1,0,0] neg_hi:[1,0,0]
	v_pk_fma_f32 v[2:3], v[98:99], v[46:47], v[6:7] op_sel_hi:[0,1,1] neg_lo:[1,0,0] neg_hi:[1,0,0]
	ds_read_b128 v[8:11], v246 offset:35840
	v_pk_mul_f32 v[96:97], v[0:1], v[60:61]
	ds_read_b128 v[12:15], v246 offset:36096
	v_pk_fma_f32 v[96:97], v[2:3], v[62:63], v[96:97]
	v_pk_fma_f32 v[4:5], v[0:1], v[52:53], v[0:1] neg_lo:[1,0,0] neg_hi:[1,0,0]
	v_add_f32_e32 v98, v96, v97
	v_pk_fma_f32 v[6:7], v[2:3], v[54:55], v[2:3] neg_lo:[1,0,0] neg_hi:[1,0,0]
	ds_read_b128 v[16:19], v246 offset:36352
	v_add_f32_dpp v98, v98, v98 quad_perm:[1,0,3,2] row_mask:0xf bank_mask:0xf bound_ctrl:1
	v_pk_fma_f32 v[4:5], v[56:57], v[90:91], v[4:5] op_sel_hi:[1,0,1]
	v_pk_fma_f32 v[6:7], v[58:59], v[90:91], v[6:7] op_sel_hi:[1,0,1]
	v_add_f32_dpp v98, v98, v98 quad_perm:[2,3,0,1] row_mask:0xf bank_mask:0xf bound_ctrl:1
	v_pk_mul_f32 v[100:101], v[0:1], v[28:29]
	v_pk_fma_f32 v[100:101], v[2:3], v[30:31], v[100:101]
	v_add_f32_dpp v98, v98, v98 row_half_mirror row_mask:0xf bank_mask:0xf bound_ctrl:1
	v_add_f32_e32 v103, v100, v101
	v_add_f32_dpp v108, v108, v108 quad_perm:[1,0,3,2] row_mask:0xf bank_mask:0xf bound_ctrl:1
	v_add_f32_dpp v98, v98, v98 row_mirror row_mask:0xf bank_mask:0xf bound_ctrl:1
	ds_read_b128 v[20:23], v246 offset:36608
	ds_read_b128 v[24:27], v246 offset:36864
	ds_read_b128 v[92:95], v247 offset:1328
	v_add_f32_dpp v108, v108, v108 quad_perm:[2,3,0,1] row_mask:0xf bank_mask:0xf bound_ctrl:1
	v_cvt_pk_bf16_f32 v109, v108, v108
	global_store_short v249, v109, s[10:11]
	s_waitcnt lgkmcnt(7)
	v_pk_fma_f32 v[0:1], v[98:99], v[64:65], v[4:5] op_sel_hi:[0,1,1] neg_lo:[1,0,0] neg_hi:[1,0,0]
	v_pk_fma_f32 v[2:3], v[98:99], v[66:67], v[6:7] op_sel_hi:[0,1,1] neg_lo:[1,0,0] neg_hi:[1,0,0]
	ds_read_b128 v[28:31], v246 offset:37120
	v_pk_mul_f32 v[96:97], v[0:1], v[80:81]
	ds_read_b128 v[32:35], v246 offset:37376
	v_pk_fma_f32 v[96:97], v[2:3], v[82:83], v[96:97]
	v_pk_fma_f32 v[4:5], v[0:1], v[72:73], v[0:1] neg_lo:[1,0,0] neg_hi:[1,0,0]
	v_add_f32_e32 v98, v96, v97
	v_pk_fma_f32 v[6:7], v[2:3], v[74:75], v[2:3] neg_lo:[1,0,0] neg_hi:[1,0,0]
	ds_read_b128 v[36:39], v246 offset:37632
	v_add_f32_dpp v98, v98, v98 quad_perm:[1,0,3,2] row_mask:0xf bank_mask:0xf bound_ctrl:1
	v_pk_fma_f32 v[4:5], v[76:77], v[90:91], v[4:5] op_sel:[0,1,0] op_sel_hi:[1,1,1]
	v_pk_fma_f32 v[6:7], v[78:79], v[90:91], v[6:7] op_sel:[0,1,0] op_sel_hi:[1,1,1]
	v_add_f32_dpp v98, v98, v98 quad_perm:[2,3,0,1] row_mask:0xf bank_mask:0xf bound_ctrl:1
	v_pk_mul_f32 v[100:101], v[0:1], v[48:49]
	v_pk_fma_f32 v[100:101], v[2:3], v[50:51], v[100:101]
	v_add_f32_dpp v98, v98, v98 row_half_mirror row_mask:0xf bank_mask:0xf bound_ctrl:1
	v_add_f32_e32 v104, v100, v101
	s_add_u32 s10, s10, 0x2000
	s_addc_u32 s11, s11, 0
	v_add_f32_dpp v98, v98, v98 row_mirror row_mask:0xf bank_mask:0xf bound_ctrl:1
	ds_read_b128 v[40:43], v246 offset:37888
	ds_read_b128 v[44:47], v246 offset:38144
	s_waitcnt lgkmcnt(5)
	v_pk_fma_f32 v[0:1], v[98:99], v[84:85], v[4:5] op_sel_hi:[0,1,1] neg_lo:[1,0,0] neg_hi:[1,0,0]
	v_pk_fma_f32 v[2:3], v[98:99], v[86:87], v[6:7] op_sel_hi:[0,1,1] neg_lo:[1,0,0] neg_hi:[1,0,0]
	ds_read_b128 v[48:51], v246 offset:38400
	v_pk_mul_f32 v[96:97], v[0:1], v[20:21]
	ds_read_b128 v[52:55], v246 offset:38656
	v_pk_fma_f32 v[96:97], v[2:3], v[22:23], v[96:97]
	v_pk_fma_f32 v[4:5], v[0:1], v[12:13], v[0:1] neg_lo:[1,0,0] neg_hi:[1,0,0]
	v_add_f32_e32 v98, v96, v97
	v_pk_fma_f32 v[6:7], v[2:3], v[14:15], v[2:3] neg_lo:[1,0,0] neg_hi:[1,0,0]
	ds_read_b128 v[56:59], v246 offset:38912
	v_add_f32_dpp v98, v98, v98 quad_perm:[1,0,3,2] row_mask:0xf bank_mask:0xf bound_ctrl:1
	v_pk_fma_f32 v[4:5], v[16:17], v[92:93], v[4:5] op_sel_hi:[1,0,1]
	v_pk_fma_f32 v[6:7], v[18:19], v[92:93], v[6:7] op_sel_hi:[1,0,1]
	v_add_f32_dpp v98, v98, v98 quad_perm:[2,3,0,1] row_mask:0xf bank_mask:0xf bound_ctrl:1
	v_pk_mul_f32 v[100:101], v[0:1], v[68:69]
	v_pk_fma_f32 v[100:101], v[2:3], v[70:71], v[100:101]
	v_add_f32_dpp v98, v98, v98 row_half_mirror row_mask:0xf bank_mask:0xf bound_ctrl:1
	v_add_f32_e32 v105, v100, v101
	ds_read_b128 v[60:63], v246 offset:39168
	v_add_f32_dpp v98, v98, v98 row_mirror row_mask:0xf bank_mask:0xf bound_ctrl:1
	ds_read_b128 v[64:67], v246 offset:39424
	v_add_f32_dpp v106, v102, v102 row_mirror row_mask:0xf bank_mask:0x3 bound_ctrl:1
	v_add_f32_dpp v107, v104, v104 row_mirror row_mask:0xf bank_mask:0x3 bound_ctrl:1
	v_add_f32_dpp v106, v103, v103 row_mirror row_mask:0xf bank_mask:0xc bound_ctrl:1
	s_waitcnt lgkmcnt(5)
	v_pk_fma_f32 v[0:1], v[98:99], v[24:25], v[4:5] op_sel_hi:[0,1,1] neg_lo:[1,0,0] neg_hi:[1,0,0]
	v_pk_fma_f32 v[2:3], v[98:99], v[26:27], v[6:7] op_sel_hi:[0,1,1] neg_lo:[1,0,0] neg_hi:[1,0,0]
	ds_read_b128 v[68:71], v246 offset:39680
	v_pk_mul_f32 v[96:97], v[0:1], v[40:41]
	ds_read_b128 v[72:75], v246 offset:39936
	v_pk_fma_f32 v[96:97], v[2:3], v[42:43], v[96:97]
	v_pk_fma_f32 v[4:5], v[0:1], v[32:33], v[0:1] neg_lo:[1,0,0] neg_hi:[1,0,0]
	v_add_f32_e32 v98, v96, v97
	v_pk_fma_f32 v[6:7], v[2:3], v[34:35], v[2:3] neg_lo:[1,0,0] neg_hi:[1,0,0]
	ds_read_b128 v[76:79], v246 offset:40192
	v_add_f32_dpp v98, v98, v98 quad_perm:[1,0,3,2] row_mask:0xf bank_mask:0xf bound_ctrl:1
	v_pk_fma_f32 v[4:5], v[36:37], v[92:93], v[4:5] op_sel:[0,1,0] op_sel_hi:[1,1,1]
	v_pk_fma_f32 v[6:7], v[38:39], v[92:93], v[6:7] op_sel:[0,1,0] op_sel_hi:[1,1,1]
	v_add_f32_dpp v98, v98, v98 quad_perm:[2,3,0,1] row_mask:0xf bank_mask:0xf bound_ctrl:1
	v_pk_mul_f32 v[100:101], v[0:1], v[8:9]
	v_pk_fma_f32 v[100:101], v[2:3], v[10:11], v[100:101]
	v_add_f32_dpp v98, v98, v98 row_half_mirror row_mask:0xf bank_mask:0xf bound_ctrl:1
	v_add_f32_e32 v250, v100, v101
	v_add_f32_dpp v107, v105, v105 row_mirror row_mask:0xf bank_mask:0xc bound_ctrl:1
	v_add_f32_dpp v98, v98, v98 row_mirror row_mask:0xf bank_mask:0xf bound_ctrl:1
	ds_read_b128 v[80:83], v246 offset:40448
	ds_read_b128 v[84:87], v246 offset:40704
	v_add_f32_dpp v108, v106, v106 row_half_mirror row_mask:0xf bank_mask:0x5 bound_ctrl:1
	v_add_f32_dpp v108, v107, v107 row_half_mirror row_mask:0xf bank_mask:0xa bound_ctrl:1
	s_waitcnt lgkmcnt(15)
	s_barrier
	s_waitcnt lgkmcnt(5)
	v_pk_fma_f32 v[0:1], v[98:99], v[44:45], v[4:5] op_sel_hi:[0,1,1] neg_lo:[1,0,0] neg_hi:[1,0,0]
	v_pk_fma_f32 v[2:3], v[98:99], v[46:47], v[6:7] op_sel_hi:[0,1,1] neg_lo:[1,0,0] neg_hi:[1,0,0]
	ds_read_b128 v[8:11], v246 offset:0
	v_pk_mul_f32 v[96:97], v[0:1], v[60:61]
	ds_read_b128 v[12:15], v246 offset:256
	v_pk_fma_f32 v[96:97], v[2:3], v[62:63], v[96:97]
	v_pk_fma_f32 v[4:5], v[0:1], v[52:53], v[0:1] neg_lo:[1,0,0] neg_hi:[1,0,0]
	v_add_f32_e32 v98, v96, v97
	v_pk_fma_f32 v[6:7], v[2:3], v[54:55], v[2:3] neg_lo:[1,0,0] neg_hi:[1,0,0]
	ds_read_b128 v[16:19], v246 offset:512
	v_add_f32_dpp v98, v98, v98 quad_perm:[1,0,3,2] row_mask:0xf bank_mask:0xf bound_ctrl:1
	v_pk_fma_f32 v[4:5], v[56:57], v[94:95], v[4:5] op_sel_hi:[1,0,1]
	v_pk_fma_f32 v[6:7], v[58:59], v[94:95], v[6:7] op_sel_hi:[1,0,1]
	v_add_f32_dpp v98, v98, v98 quad_perm:[2,3,0,1] row_mask:0xf bank_mask:0xf bound_ctrl:1
	v_pk_mul_f32 v[100:101], v[0:1], v[28:29]
	v_pk_fma_f32 v[100:101], v[2:3], v[30:31], v[100:101]
	v_add_f32_dpp v98, v98, v98 row_half_mirror row_mask:0xf bank_mask:0xf bound_ctrl:1
	v_add_f32_e32 v251, v100, v101
	v_add_f32_dpp v108, v108, v108 quad_perm:[1,0,3,2] row_mask:0xf bank_mask:0xf bound_ctrl:1
	v_add_f32_dpp v98, v98, v98 row_mirror row_mask:0xf bank_mask:0xf bound_ctrl:1
	ds_read_b128 v[20:23], v246 offset:768
	ds_read_b128 v[24:27], v246 offset:1024
	ds_read_b128 v[88:91], v247 offset:0
	v_add_f32_dpp v108, v108, v108 quad_perm:[2,3,0,1] row_mask:0xf bank_mask:0xf bound_ctrl:1
	v_cvt_pk_bf16_f32 v109, v108, v108
	global_store_short v249, v109, s[10:11]
	s_waitcnt lgkmcnt(6)
	v_pk_fma_f32 v[0:1], v[98:99], v[64:65], v[4:5] op_sel_hi:[0,1,1] neg_lo:[1,0,0] neg_hi:[1,0,0]
	v_pk_fma_f32 v[2:3], v[98:99], v[66:67], v[6:7] op_sel_hi:[0,1,1] neg_lo:[1,0,0] neg_hi:[1,0,0]
	ds_read_b128 v[28:31], v246 offset:1280
	v_pk_mul_f32 v[96:97], v[0:1], v[80:81]
	ds_read_b128 v[32:35], v246 offset:1536
	v_pk_fma_f32 v[96:97], v[2:3], v[82:83], v[96:97]
	v_pk_fma_f32 v[4:5], v[0:1], v[72:73], v[0:1] neg_lo:[1,0,0] neg_hi:[1,0,0]
	v_add_f32_e32 v98, v96, v97
	v_pk_fma_f32 v[6:7], v[2:3], v[74:75], v[2:3] neg_lo:[1,0,0] neg_hi:[1,0,0]
	ds_read_b128 v[36:39], v246 offset:1792
	v_add_f32_dpp v98, v98, v98 quad_perm:[1,0,3,2] row_mask:0xf bank_mask:0xf bound_ctrl:1
	v_pk_fma_f32 v[4:5], v[76:77], v[94:95], v[4:5] op_sel:[0,1,0] op_sel_hi:[1,1,1]
	v_pk_fma_f32 v[6:7], v[78:79], v[94:95], v[6:7] op_sel:[0,1,0] op_sel_hi:[1,1,1]
	v_add_f32_dpp v98, v98, v98 quad_perm:[2,3,0,1] row_mask:0xf bank_mask:0xf bound_ctrl:1
	v_pk_mul_f32 v[100:101], v[0:1], v[48:49]
	v_pk_fma_f32 v[100:101], v[2:3], v[50:51], v[100:101]
	v_add_f32_dpp v98, v98, v98 row_half_mirror row_mask:0xf bank_mask:0xf bound_ctrl:1
	v_add_f32_e32 v252, v100, v101
	s_add_u32 s10, s10, 0x2000
	s_addc_u32 s11, s11, 0
	v_add_f32_dpp v98, v98, v98 row_mirror row_mask:0xf bank_mask:0xf bound_ctrl:1
	ds_read_b128 v[40:43], v246 offset:2048
	ds_read_b128 v[44:47], v246 offset:2304
	s_waitcnt lgkmcnt(5)
	v_pk_fma_f32 v[0:1], v[98:99], v[84:85], v[4:5] op_sel_hi:[0,1,1] neg_lo:[1,0,0] neg_hi:[1,0,0]
	v_pk_fma_f32 v[2:3], v[98:99], v[86:87], v[6:7] op_sel_hi:[0,1,1] neg_lo:[1,0,0] neg_hi:[1,0,0]
	ds_read_b128 v[48:51], v246 offset:2560
	v_pk_mul_f32 v[96:97], v[0:1], v[20:21]
	ds_read_b128 v[52:55], v246 offset:2816
	v_pk_fma_f32 v[96:97], v[2:3], v[22:23], v[96:97]
	v_pk_fma_f32 v[4:5], v[0:1], v[12:13], v[0:1] neg_lo:[1,0,0] neg_hi:[1,0,0]
	v_add_f32_e32 v98, v96, v97
	v_pk_fma_f32 v[6:7], v[2:3], v[14:15], v[2:3] neg_lo:[1,0,0] neg_hi:[1,0,0]
	ds_read_b128 v[56:59], v246 offset:3072
	v_add_f32_dpp v98, v98, v98 quad_perm:[1,0,3,2] row_mask:0xf bank_mask:0xf bound_ctrl:1
	v_pk_fma_f32 v[4:5], v[16:17], v[88:89], v[4:5] op_sel_hi:[1,0,1]
	v_pk_fma_f32 v[6:7], v[18:19], v[88:89], v[6:7] op_sel_hi:[1,0,1]
	v_add_f32_dpp v98, v98, v98 quad_perm:[2,3,0,1] row_mask:0xf bank_mask:0xf bound_ctrl:1
	v_pk_mul_f32 v[100:101], v[0:1], v[68:69]
	v_pk_fma_f32 v[100:101], v[2:3], v[70:71], v[100:101]
	v_add_f32_dpp v98, v98, v98 row_half_mirror row_mask:0xf bank_mask:0xf bound_ctrl:1
	v_add_f32_e32 v253, v100, v101
	ds_read_b128 v[60:63], v246 offset:3328
	v_add_f32_dpp v98, v98, v98 row_mirror row_mask:0xf bank_mask:0xf bound_ctrl:1
	ds_read_b128 v[64:67], v246 offset:3584
	v_add_f32_dpp v106, v250, v250 row_mirror row_mask:0xf bank_mask:0x3 bound_ctrl:1
	v_add_f32_dpp v107, v252, v252 row_mirror row_mask:0xf bank_mask:0x3 bound_ctrl:1
	v_add_f32_dpp v106, v251, v251 row_mirror row_mask:0xf bank_mask:0xc bound_ctrl:1
	v_add_f32_dpp v107, v253, v253 row_mirror row_mask:0xf bank_mask:0xc bound_ctrl:1
	s_nop 0
	v_add_f32_dpp v108, v106, v106 row_half_mirror row_mask:0xf bank_mask:0x5 bound_ctrl:1
	v_add_f32_dpp v108, v107, v107 row_half_mirror row_mask:0xf bank_mask:0xa bound_ctrl:1
	s_nop 1
	v_add_f32_dpp v108, v108, v108 quad_perm:[1,0,3,2] row_mask:0xf bank_mask:0xf bound_ctrl:1
	s_nop 1
	v_add_f32_dpp v108, v108, v108 quad_perm:[2,3,0,1] row_mask:0xf bank_mask:0xf bound_ctrl:1
	v_cvt_pk_bf16_f32 v109, v108, v108
	global_store_short v249, v109, s[10:11]
	s_add_u32 s10, s10, 0x2000
	s_addc_u32 s11, s11, 0
	s_add_i32 s12, s12, 1
	s_cmp_lt_u32 s12, 0x80
	s_cbranch_scc1 .Lscan_iter
	s_waitcnt vmcnt(0) lgkmcnt(0)
	s_barrier
	s_branch .LBB0_587
